# final RMSNorm: row-invariant gain vectors loaded once before the row loop, no per-chunk load/store round trips
# baseline (speedup 1.0000x reference)
; __device__ __forceinline__ int tid_of(int wv) { int t = wv * 64 + lane_id(); asm volatile("" : "+v"(t)); return t; }
; __device__ __forceinline__ int bidx() { int t = blockIdx.x; asm volatile("" : "+s"(t)); return t; }
; __device__ __forceinline__ void phase_final(const PP& p) {
;     const int lane = tid_of(p.wv) & 63, gw = bidx() * 8 + (tid_of(p.wv) >> 6), nw = gridDim.x * 8;
;     const float* gain = p.in[I_FG];
;     for (int r = gw; r < NB * SEQ; r += nw) {
;         float* src = p.out + (size_t)r * DM;
;         f32x4 v[4]; float ss = 0.f;
; #pragma unroll
;         for (int i = 0; i < 4; ++i) { v[i] = *(const f32x4*)(src + i * 256 + lane * 4); ss += v[i][0] * v[i][0] + v[i][1] * v[i][1] + v[i][2] * v[i][2] + v[i][3] * v[i][3]; }
;         ss = red64(ss);
;         const float rs = __builtin_amdgcn_rsqf(ss * (1.f / 1024.f) + 1e-6f);
; #pragma unroll
;         for (int i = 0; i < 4; ++i) { const int c = i * 256 + lane * 4; const f32x4 gv = *(const f32x4*)(gain + c); *(f32x4*)(src + c) = v[i] * rs * gv; }
;     }
; }
.LBB0_1420:
	s_add_i32 s0, 0, 0x27c30
	v_mov_b32_e32 v5, v162
	v_readlane_b32 s1, v252, 0
	v_mov_b32_e32 v0, s0
	ds_read_b64 v[0:1], v0
	s_lshl_b32 s0, s1, 3
	v_ashrrev_i32_e32 v2, 6, v162
	v_add_u32_e32 v4, s0, v2
	s_mov_b32 s1, 0x8000
	s_waitcnt lgkmcnt(0)
	v_readfirstlane_b32 s3, v1
	v_readfirstlane_b32 s2, v0
	v_cmp_gt_i32_e32 vcc, s1, v4
	s_and_saveexec_b64 s[4:5], vcc
	v_readlane_b32 s6, v254, 7
	v_readlane_b32 s7, v254, 8
	s_cbranch_execz .LBB0_1423
	v_ashrrev_i32_e32 v3, 31, v2
	s_ashr_i32 s1, s0, 31
	v_lshl_add_u64 v[2:3], v[2:3], 0, s[0:1]
	v_lshlrev_b32_e32 v0, 4, v5
	v_lshlrev_b64 v[2:3], 12, v[2:3]
	v_and_b32_e32 v5, 63, v5
	v_readlane_b32 s0, v252, 1
	v_lshl_or_b32 v2, v5, 4, v2
	v_readlane_b32 s1, v252, 2
	v_and_b32_e32 v0, 0x3f0, v0
	v_mov_b32_e32 v1, 0
	v_lshl_add_u64 v[2:3], s[0:1], 0, v[2:3]
	s_mov_b64 s[0:1], 0x800
	v_lshl_add_u64 v[0:1], s[2:3], 0, v[0:1]
	v_lshl_add_u64 v[2:3], v[2:3], 0, s[0:1]
	s_lshl_b64 s[0:1], s[6:7], 12
	s_mov_b64 s[2:3], 0
	v_mov_b32_e32 v5, 0x358637bd
	s_movk_i32 s4, 0x7fff
	global_load_dwordx4 v[36:39], v[0:1], off
	global_load_dwordx4 v[40:43], v[0:1], off offset:1024
	global_load_dwordx4 v[44:47], v[0:1], off offset:2048
	global_load_dwordx4 v[48:51], v[0:1], off offset:3072
	s_waitcnt vmcnt(0)
.LBB0_1422:
	global_load_dwordx4 v[6:9], v[2:3], off offset:-2048
	global_load_dwordx4 v[10:13], v[2:3], off offset:-1024
	global_load_dwordx4 v[14:17], v[2:3], off
	global_load_dwordx4 v[18:21], v[2:3], off offset:1024
	v_add_u32_e32 v4, s6, v4
	v_cmp_lt_i32_e32 vcc, s4, v4
	s_or_b64 s[2:3], vcc, s[2:3]
	s_waitcnt vmcnt(3)
	v_mul_f32_e32 v34, v7, v7
	s_waitcnt vmcnt(2)
	v_mul_f32_e32 v35, v11, v11
	s_waitcnt vmcnt(1)
	v_mov_b32_e32 v28, v15
	s_waitcnt vmcnt(0)
	v_mov_b32_e32 v29, v19
	v_mov_b32_e32 v26, v14
	v_mov_b32_e32 v27, v18
	v_fmac_f32_e32 v34, v6, v6
	v_fmac_f32_e32 v35, v10, v10
	v_pk_mul_f32 v[28:29], v[28:29], v[28:29]
	v_mov_b32_e32 v30, v16
	v_mov_b32_e32 v31, v20
	v_fmac_f32_e32 v34, v8, v8
	v_fmac_f32_e32 v35, v12, v12
	v_pk_fma_f32 v[26:27], v[26:27], v[26:27], v[28:29]
	v_mov_b32_e32 v32, v17
	v_mov_b32_e32 v33, v21
	v_fmac_f32_e32 v34, v9, v9
	v_fmac_f32_e32 v35, v13, v13
	v_pk_fma_f32 v[26:27], v[30:31], v[30:31], v[26:27]
	v_add_f32_e32 v28, v34, v35
	v_pk_fma_f32 v[26:27], v[32:33], v[32:33], v[26:27]
	s_nop 0
	v_add_f32_e32 v26, v28, v26
	v_add_f32_e32 v26, v26, v27
	ds_bpermute_b32 v27, v164, v26
	s_waitcnt lgkmcnt(0)
	v_add_f32_e32 v26, v26, v27
	ds_bpermute_b32 v27, v165, v26
	s_waitcnt lgkmcnt(0)
	v_add_f32_e32 v26, v26, v27
	ds_bpermute_b32 v27, v166, v26
	s_waitcnt lgkmcnt(0)
	v_add_f32_e32 v26, v26, v27
	ds_bpermute_b32 v27, v167, v26
	s_waitcnt lgkmcnt(0)
	v_add_f32_e32 v26, v26, v27
	ds_bpermute_b32 v27, v168, v26
	s_waitcnt lgkmcnt(0)
	v_add_f32_e32 v26, v26, v27
	ds_bpermute_b32 v27, v169, v26
	s_waitcnt lgkmcnt(0)
	v_add_f32_e32 v26, v26, v27
	v_fmamk_f32 v26, v26, 0x3a800000, v5
	v_rsq_f32_e32 v26, v26
	s_nop 0
	v_pk_mul_f32 v[6:7], v[6:7], v[26:27] op_sel_hi:[1,0]
	v_pk_mul_f32 v[8:9], v[8:9], v[26:27] op_sel_hi:[1,0]
	v_pk_mul_f32 v[6:7], v[36:37], v[6:7]
	v_pk_mul_f32 v[8:9], v[38:39], v[8:9]
	global_store_dwordx4 v[2:3], v[6:9], off offset:-2048
	v_pk_mul_f32 v[10:11], v[10:11], v[26:27] op_sel_hi:[1,0]
	v_pk_mul_f32 v[12:13], v[12:13], v[26:27] op_sel_hi:[1,0]
	v_pk_mul_f32 v[10:11], v[40:41], v[10:11]
	v_pk_mul_f32 v[12:13], v[42:43], v[12:13]
	global_store_dwordx4 v[2:3], v[10:13], off offset:-1024
	v_pk_mul_f32 v[14:15], v[14:15], v[26:27] op_sel_hi:[1,0]
	v_pk_mul_f32 v[16:17], v[16:17], v[26:27] op_sel_hi:[1,0]
	v_pk_mul_f32 v[14:15], v[44:45], v[14:15]
	v_pk_mul_f32 v[16:17], v[46:47], v[16:17]
	global_store_dwordx4 v[2:3], v[14:17], off
	v_pk_mul_f32 v[18:19], v[18:19], v[26:27] op_sel_hi:[1,0]
	v_pk_mul_f32 v[20:21], v[20:21], v[26:27] op_sel_hi:[1,0]
	v_pk_mul_f32 v[18:19], v[48:49], v[18:19]
	v_pk_mul_f32 v[20:21], v[50:51], v[20:21]
	global_store_dwordx4 v[2:3], v[18:21], off offset:1024
	v_lshl_add_u64 v[2:3], v[2:3], 0, s[0:1]
	s_andn2_b64 exec, exec, s[2:3]
	s_cbranch_execnz .LBB0_1422
